# E4b + MLA: step-2 QK accumulators initialised straight from the running-reference registers (drops 8 v_mov_b64 per step pair)
# baseline (speedup 1.0000x reference)
.LBB0_830:
	s_nop 2
	v_max_f32_e32 v80, v113, v113
	v_max_f32_e32 v81, v112, v112
	v_max_f32_e32 v80, v81, v80
	v_max3_f32 v80, v80, v114, v115
	v_max3_f32 v80, v80, v116, v117
	v_max3_f32 v80, v80, v118, v119
	v_max3_f32 v80, v80, v120, v121
	v_max3_f32 v80, v80, v122, v123
	v_max3_f32 v80, v80, v124, v125
	v_max3_f32 v80, v80, v126, v127
	v_max3_f32 v80, v80, v96, v97
	v_max3_f32 v80, v80, v98, v99
	v_max3_f32 v80, v80, v100, v101
	v_max3_f32 v80, v80, v102, v103
	v_max3_f32 v80, v80, v104, v105
	v_max3_f32 v80, v80, v106, v107
	v_max3_f32 v80, v80, v108, v109
	v_max3_f32 v80, v80, v110, v111
	v_mov_b32_e32 v81, v80
	s_nop 1
	v_permlane32_swap_b32_e32 v80, v81
	v_max_f32_e32 v81, v81, v81
	v_max_f32_e32 v80, v80, v80
	s_cmp_lg_u32 s5, 0
	v_max_f32_e32 v80, v80, v81
	s_cbranch_scc0 .LBB0_835
	v_cmp_ge_f32_e32 vcc, s36, v80
	s_cmp_lg_u64 vcc, exec
	s_mov_b64 s[86:87], 0
	s_mov_b64 s[84:85], 0
	s_cbranch_scc1 .LBB0_836
	v_mov_b32_e32 v231, 1.0
	s_branch .LBB0_842

.LBB0_844:
	ds_read_b128 v[114:117], v227 offset:49152
	ds_read_b128 v[118:121], v227 offset:57344
	ds_read_b128 v[122:125], v228 offset:49152
	ds_read_b128 v[232:235], v228 offset:57344
	s_add_i32 s14, s82, -1
	s_setprio 1
	ds_read_b128 v[236:239], v229 offset:49152
	ds_read_b128 v[240:243], v229 offset:57344
	s_waitcnt lgkmcnt(5)
	v_mfma_f32_32x32x16_bf16 v[96:111], v[114:117], v[130:133], v[64:79]
	s_waitcnt lgkmcnt(4)
	v_mfma_f32_32x32x16_bf16 v[80:95], v[118:121], v[130:133], v[64:79]
	ds_read_b128 v[114:117], v230 offset:49152
	ds_read_b128 v[118:121], v230 offset:57344
	s_waitcnt lgkmcnt(5)
	v_mfma_f32_32x32x16_bf16 v[96:111], v[122:125], v[134:137], v[96:111]
	s_waitcnt lgkmcnt(4)
	v_mfma_f32_32x32x16_bf16 v[80:95], v[232:235], v[134:137], v[80:95]
	ds_read_b128 v[122:125], v227 offset:49280
	ds_read_b128 v[232:235], v227 offset:57472
	s_waitcnt lgkmcnt(5)
	v_mfma_f32_32x32x16_bf16 v[96:111], v[236:239], v[138:141], v[96:111]
	s_waitcnt lgkmcnt(4)
	v_mfma_f32_32x32x16_bf16 v[80:95], v[240:243], v[138:141], v[80:95]
	ds_read_b128 v[236:239], v228 offset:49280
	ds_read_b128 v[240:243], v228 offset:57472
	s_waitcnt lgkmcnt(5)
	v_mfma_f32_32x32x16_bf16 v[96:111], v[114:117], v[142:145], v[96:111]
	s_waitcnt lgkmcnt(4)
	v_mfma_f32_32x32x16_bf16 v[80:95], v[118:121], v[142:145], v[80:95]
	ds_read_b128 v[114:117], v229 offset:49280
	ds_read_b128 v[118:121], v229 offset:57472
	s_waitcnt lgkmcnt(5)
	v_mfma_f32_32x32x16_bf16 v[96:111], v[122:125], v[162:165], v[96:111]
	s_waitcnt lgkmcnt(4)
	v_mfma_f32_32x32x16_bf16 v[80:95], v[232:235], v[162:165], v[80:95]
	ds_read_b128 v[122:125], v230 offset:49280
	ds_read_b128 v[232:235], v230 offset:57472
	s_waitcnt lgkmcnt(5)
	v_mfma_f32_32x32x16_bf16 v[96:111], v[236:239], v[166:169], v[96:111]
	s_waitcnt lgkmcnt(4)
	v_mfma_f32_32x32x16_bf16 v[80:95], v[240:243], v[166:169], v[80:95]
	v_add_u32_e32 v126, v224, v220
	ds_read_b128 v[236:239], v126 offset:4096
	ds_read_b128 v[240:243], v126
	ds_read_b128 v[244:247], v213
	s_waitcnt lgkmcnt(6)
	v_mfma_f32_32x32x16_bf16 v[96:111], v[114:117], v[170:173], v[96:111]
	s_waitcnt lgkmcnt(5)
	v_mfma_f32_32x32x16_bf16 v[80:95], v[118:121], v[170:173], v[80:95]
	v_add_u32_e32 v118, v224, v221
	ds_read_b128 v[114:117], v118 offset:4096
	ds_read_b128 v[118:121], v118
	ds_read_b128 v[248:251], v213 offset:1024
	s_waitcnt lgkmcnt(7)
	v_mfma_f32_32x32x16_bf16 v[96:111], v[122:125], v[174:177], v[96:111]
	s_waitcnt lgkmcnt(6)
	v_mfma_f32_32x32x16_bf16 v[80:95], v[232:235], v[174:177], v[80:95]
	v_add_u32_e32 v126, v224, v222
	ds_read_b128 v[122:125], v126 offset:4096
	ds_read_b128 v[232:235], v126
	ds_read_b128 v[178:181], v213 offset:2048
	s_waitcnt lgkmcnt(6)
	v_mfma_f32_32x32x16_bf16 v[96:111], v[240:243], v[244:247], v[96:111]
	v_mfma_f32_32x32x16_bf16 v[80:95], v[236:239], v[244:247], v[80:95]
	v_add_u32_e32 v126, v224, v223
	ds_read_b128 v[236:239], v126 offset:4096
	ds_read_b128 v[240:243], v126
	ds_read_b128 v[244:247], v213 offset:3072
	s_waitcnt lgkmcnt(6)
	v_mfma_f32_32x32x16_bf16 v[96:111], v[118:121], v[248:251], v[96:111]
	v_mfma_f32_32x32x16_bf16 v[80:95], v[114:117], v[248:251], v[80:95]
	s_waitcnt lgkmcnt(3)
	v_mfma_f32_32x32x16_bf16 v[96:111], v[232:235], v[178:181], v[96:111]
	v_mfma_f32_32x32x16_bf16 v[80:95], v[122:125], v[178:181], v[80:95]
	s_waitcnt lgkmcnt(0)
	v_mfma_f32_32x32x16_bf16 v[96:111], v[240:243], v[244:247], v[96:111]
	v_mfma_f32_32x32x16_bf16 v[80:95], v[236:239], v[244:247], v[80:95]
	s_setprio 0
	s_cmp_le_i32 s14, s12
	s_cselect_b64 s[14:15], -1, 0
	s_cmp_gt_i32 s50, s22
	s_cselect_b64 s[44:45], -1, 0
	s_and_b64 s[14:15], s[14:15], s[44:45]
	s_and_b64 vcc, exec, s[14:15]
	s_cbranch_vccnz .LBB0_846
	v_add_u32_e32 v114, -5, v225
	v_cmp_gt_u32_e32 vcc, s35, v114
	v_subrev_u32_e32 v114, 37, v225
	s_nop 0
	v_cndmask_b32_e32 v96, v202, v96, vcc
	v_cmp_gt_u32_e32 vcc, s35, v114
	v_add_u32_e32 v114, -6, v225
	s_nop 0
	v_cndmask_b32_e32 v80, v202, v80, vcc
	v_cmp_gt_u32_e32 vcc, s35, v114
	v_subrev_u32_e32 v114, 38, v225
	s_nop 0
	v_cndmask_b32_e32 v97, v202, v97, vcc
	v_cmp_gt_u32_e32 vcc, s35, v114
	v_add_u32_e32 v114, -7, v225
	s_nop 0
	v_cndmask_b32_e32 v81, v202, v81, vcc
	v_cmp_gt_u32_e32 vcc, s35, v114
	v_subrev_u32_e32 v114, 39, v225
	s_nop 0
	v_cndmask_b32_e32 v98, v202, v98, vcc
	v_cmp_gt_u32_e32 vcc, s35, v114
	v_add_u32_e32 v114, -8, v225
	s_nop 0
	v_cndmask_b32_e32 v82, v202, v82, vcc
	v_cmp_gt_u32_e32 vcc, s35, v114
	v_subrev_u32_e32 v114, 40, v225
	s_nop 0
	v_cndmask_b32_e32 v99, v202, v99, vcc
	v_cmp_gt_u32_e32 vcc, s35, v114
	v_add_u32_e32 v114, -13, v225
	s_nop 0
	v_cndmask_b32_e32 v83, v202, v83, vcc
	v_cmp_gt_u32_e32 vcc, s35, v114
	v_subrev_u32_e32 v114, 45, v225
	s_nop 0
	v_cndmask_b32_e32 v100, v202, v100, vcc
	v_cmp_gt_u32_e32 vcc, s35, v114
	v_add_u32_e32 v114, -14, v225
	s_nop 0
	v_cndmask_b32_e32 v84, v202, v84, vcc
	v_cmp_gt_u32_e32 vcc, s35, v114
	v_subrev_u32_e32 v114, 46, v225
	s_nop 0
	v_cndmask_b32_e32 v101, v202, v101, vcc
	v_cmp_gt_u32_e32 vcc, s35, v114
	v_add_u32_e32 v114, -15, v225
	s_nop 0
	v_cndmask_b32_e32 v85, v202, v85, vcc
	v_cmp_gt_u32_e32 vcc, s35, v114
	v_subrev_u32_e32 v114, 47, v225
	s_nop 0
	v_cndmask_b32_e32 v102, v202, v102, vcc
	v_cmp_gt_u32_e32 vcc, s35, v114
	v_add_u32_e32 v114, -16, v225
	s_nop 0
	v_cndmask_b32_e32 v86, v202, v86, vcc
	v_cmp_gt_u32_e32 vcc, s35, v114
	v_subrev_u32_e32 v114, 48, v225
	s_nop 0
	v_cndmask_b32_e32 v103, v202, v103, vcc
	v_cmp_gt_u32_e32 vcc, s35, v114
	v_subrev_u32_e32 v114, 21, v225
	s_nop 0
	v_cndmask_b32_e32 v87, v202, v87, vcc
	v_cmp_gt_u32_e32 vcc, s35, v114
	v_subrev_u32_e32 v114, 53, v225
	s_nop 0
	v_cndmask_b32_e32 v104, v202, v104, vcc
	v_cmp_gt_u32_e32 vcc, s35, v114
	v_subrev_u32_e32 v114, 22, v225
	s_nop 0
	v_cndmask_b32_e32 v88, v202, v88, vcc
	v_cmp_gt_u32_e32 vcc, s35, v114
	v_subrev_u32_e32 v114, 54, v225
	s_nop 0
	v_cndmask_b32_e32 v105, v202, v105, vcc
	v_cmp_gt_u32_e32 vcc, s35, v114
	v_subrev_u32_e32 v114, 23, v225
	s_nop 0
	v_cndmask_b32_e32 v89, v202, v89, vcc
	v_cmp_gt_u32_e32 vcc, s35, v114
	v_subrev_u32_e32 v114, 55, v225
	s_nop 0
	v_cndmask_b32_e32 v106, v202, v106, vcc
	v_cmp_gt_u32_e32 vcc, s35, v114
	v_subrev_u32_e32 v114, 24, v225
	s_nop 0
	v_cndmask_b32_e32 v90, v202, v90, vcc
	v_cmp_gt_u32_e32 vcc, s35, v114
	v_subrev_u32_e32 v114, 56, v225
	s_nop 0
	v_cndmask_b32_e32 v107, v202, v107, vcc
	v_cmp_gt_u32_e32 vcc, s35, v114
	v_subrev_u32_e32 v114, 29, v225
	s_nop 0
	v_cndmask_b32_e32 v91, v202, v91, vcc
	v_cmp_gt_u32_e32 vcc, s35, v114
	v_subrev_u32_e32 v114, 61, v225
	s_nop 0
	v_cndmask_b32_e32 v108, v202, v108, vcc
	v_cmp_gt_u32_e32 vcc, s35, v114
	v_subrev_u32_e32 v114, 30, v225
	s_nop 0
	v_cndmask_b32_e32 v92, v202, v92, vcc
	v_cmp_gt_u32_e32 vcc, s35, v114
	v_subrev_u32_e32 v114, 62, v225
	s_nop 0
	v_cndmask_b32_e32 v109, v202, v109, vcc
	v_cmp_gt_u32_e32 vcc, s35, v114
	v_subrev_u32_e32 v114, 31, v225
	s_nop 0
	v_cndmask_b32_e32 v93, v202, v93, vcc
	v_cmp_gt_u32_e32 vcc, s35, v114
	v_subrev_u32_e32 v114, 63, v225
	s_nop 0
	v_cndmask_b32_e32 v110, v202, v110, vcc
	v_cmp_gt_u32_e32 vcc, s35, v114
	v_subrev_u32_e32 v114, 32, v225
	s_nop 0
	v_cndmask_b32_e32 v94, v202, v94, vcc
	v_cmp_gt_u32_e32 vcc, s35, v114
	v_subrev_u32_e32 v114, 64, v225
	s_nop 0
	v_cndmask_b32_e32 v111, v202, v111, vcc
	v_cmp_gt_u32_e32 vcc, s35, v114
	s_nop 1
	v_cndmask_b32_e32 v95, v202, v95, vcc
